# down-GEMM: the unit's 8 gate loads issued in the unit header before the K-loop, no gate wait left in the epilogue
# baseline (speedup 1.0000x reference)
.LBB0_1323:
	s_lshl_b32 s54, s47, 8
	s_add_i32 s54, s54, s91
	v_and_b32_e32 v238, 15, v174
	v_or_b32_e32 v238, s54, v238
	v_lshlrev_b32_e32 v238, 2, v238
	global_load_dword v230, v238, s[8:9]
	global_load_dword v231, v238, s[8:9] offset:64
	global_load_dword v232, v238, s[8:9] offset:128
	global_load_dword v233, v238, s[8:9] offset:192
	global_load_dword v234, v238, s[8:9] offset:512
	global_load_dword v235, v238, s[8:9] offset:576
	global_load_dword v236, v238, s[8:9] offset:640
	global_load_dword v237, v238, s[8:9] offset:704
	s_lshl_b32 s48, s43, 8
	s_or_b32 s49, s48, 0x80
	s_add_u32 s50, s18, 0x100
	s_addc_u32 s51, s19, 0
	s_mov_b32 s52, -2
	s_mov_b64 s[18:19], 0
	ds_read_b128 v[16:19], v175
	ds_read_b128 v[20:23], v175 offset:1024
	ds_read_b128 v[24:27], v175 offset:2048
	ds_read_b128 v[28:31], v175 offset:3072
	ds_read_b128 v[0:3], v176
	ds_read_b128 v[4:7], v176 offset:1024
	ds_read_b128 v[8:11], v176 offset:2048
	ds_read_b128 v[12:15], v176 offset:3072
	s_cmp_eq_u32 s52, 18
	s_cselect_b64 s[22:23], -1, 0
	s_add_u32 s20, s38, s18
	s_addc_u32 s21, s39, s19
	s_mov_b32 m0, s40
	ds_read_b128 v[178:181], v177
	ds_read_b128 v[182:185], v177 offset:1024
	ds_read_b128 v[186:189], v177 offset:2048
	ds_read_b128 v[190:193], v177 offset:3072
	ds_read_b128 v[194:197], v177 offset:4096
	ds_read_b128 v[198:201], v177 offset:5120
	ds_read_b128 v[202:205], v177 offset:6144
	ds_read_b128 v[206:209], v177 offset:7168
	global_load_lds_dwordx4 v166, s[20:21]
	s_mov_b32 m0, s41
	s_nop 0
	global_load_lds_dwordx4 v170, s[20:21]
	s_waitcnt vmcnt(8)
	s_waitcnt lgkmcnt(0)
	s_barrier
	s_setprio 1
	s_waitcnt lgkmcnt(0)
	v_mfma_f32_16x16x128_f8f6f4 v[156:159], v[16:23], v[178:185], 0
	v_mfma_f32_16x16x128_f8f6f4 v[152:155], v[24:31], v[178:185], 0
	v_mfma_f32_16x16x128_f8f6f4 v[140:143], v[16:23], v[186:193], 0
	v_mfma_f32_16x16x128_f8f6f4 v[136:139], v[24:31], v[186:193], 0
	v_mfma_f32_16x16x128_f8f6f4 v[124:127], v[16:23], v[194:201], 0
	v_mfma_f32_16x16x128_f8f6f4 v[120:123], v[24:31], v[194:201], 0
	v_mfma_f32_16x16x128_f8f6f4 v[108:111], v[16:23], v[202:209], 0
	v_mfma_f32_16x16x128_f8f6f4 v[104:107], v[24:31], v[202:209], 0
	v_mfma_f32_16x16x128_f8f6f4 v[148:151], v[0:7], v[178:185], 0
	v_mfma_f32_16x16x128_f8f6f4 v[144:147], v[8:15], v[178:185], 0
	v_mfma_f32_16x16x128_f8f6f4 v[132:135], v[0:7], v[186:193], 0
	v_mfma_f32_16x16x128_f8f6f4 v[128:131], v[8:15], v[186:193], 0
	v_mfma_f32_16x16x128_f8f6f4 v[116:119], v[0:7], v[194:201], 0
	v_mfma_f32_16x16x128_f8f6f4 v[112:115], v[8:15], v[194:201], 0
	v_mfma_f32_16x16x128_f8f6f4 v[100:103], v[0:7], v[202:209], 0
	v_mfma_f32_16x16x128_f8f6f4 v[96:99], v[8:15], v[202:209], 0
	s_setprio 0
	s_barrier
	s_and_b64 s[20:21], s[16:17], s[22:23]
	s_andn2_b64 vcc, exec, s[20:21]
	s_cbranch_vccnz .Lpk3_LBB0_1326
	s_mul_i32 s57, s48, s28
	s_mul_i32 s58, s49, s28
	v_add_u32_e32 v164, s57, v247
	v_add_u32_e32 v166, s58, v247
	v_add_u32_e32 v168, 0x2c000, v164
	v_add_u32_e32 v170, 0x2c000, v166
	s_branch .Lpk3_LBB0_1327

.LBB0_1331:
	s_lshl_b32 s4, s47, 8
	v_mov_b32_e32 v8, v174
	s_add_i32 s4, s4, s91
	v_mov_b32_e32 v4, v165
	v_and_or_b32 v2, v8, 15, s4
	v_ashrrev_i32_e32 v3, 31, v2
	v_lshl_add_u64 v[0:1], v[2:3], 2, s[8:9]
	v_mov_b32_e32 v5, v165
	v_mov_b32_e32 v6, v165
	v_mov_b32_e32 v7, v165
	s_lshl_b32 s16, s46, 8
	v_lshlrev_b64 v[10:11], 10, v[2:3]
	s_ashr_i32 s17, s16, 31
	v_ashrrev_i32_e32 v0, 1, v8
	v_lshl_add_u64 v[10:11], s[88:89], 0, v[10:11]
	v_and_b32_e32 v0, -8, v0
	v_lshl_add_u64 v[10:11], v[10:11], 0, s[16:17]
	v_or_b32_e32 v8, 16, v2
	v_ashrrev_i32_e32 v1, 31, v0
	v_lshl_add_u64 v[10:11], v[10:11], 0, s[68:69]
	v_ashrrev_i32_e32 v9, 31, v8
	v_lshl_add_u64 v[10:11], v[10:11], 0, v[0:1]
	v_lshl_add_u64 v[12:13], v[8:9], 2, s[8:9]
	v_lshlrev_b64 v[8:9], 10, v[8:9]
	v_lshl_add_u64 v[8:9], s[88:89], 0, v[8:9]
	v_lshl_add_u64 v[8:9], v[8:9], 0, s[16:17]
	v_lshl_add_u64 v[8:9], v[8:9], 0, s[68:69]
	v_lshl_add_u64 v[8:9], v[8:9], 0, v[0:1]
	s_and_b64 vcc, exec, s[0:1]
	s_mov_b64 s[0:1], -1
	v_mul_f32_e32 v14, 0x3e800000, v230
	v_pk_mul_f32 v[18:19], v[156:157], v[14:15] op_sel_hi:[1,0]
	v_pk_mul_f32 v[22:23], v[152:153], v[14:15] op_sel_hi:[1,0]
	v_pk_mul_f32 v[16:17], v[158:159], v[14:15] op_sel_hi:[1,0]
	v_pk_mul_f32 v[20:21], v[154:155], v[14:15] op_sel_hi:[1,0]
	v_pk_mul_f32 v[24:25], v[150:151], v[14:15] op_sel_hi:[1,0]
	v_pk_mul_f32 v[26:27], v[148:149], v[14:15] op_sel_hi:[1,0]
	v_pk_mul_f32 v[28:29], v[146:147], v[14:15] op_sel_hi:[1,0]
	v_pk_mul_f32 v[14:15], v[144:145], v[14:15] op_sel_hi:[1,0]
	v_cvt_pk_fp8_f32 v4, v18, v19
	v_cvt_pk_fp8_f32 v5, v22, v23
	v_cvt_pk_fp8_f32 v6, v26, v27
	v_cvt_pk_fp8_f32 v7, v14, v15
	v_cvt_pk_fp8_f32 v4, v16, v17 op_sel:[0,0,1]
	v_cvt_pk_fp8_f32 v5, v20, v21 op_sel:[0,0,1]
	v_cvt_pk_fp8_f32 v6, v24, v25 op_sel:[0,0,1]
	v_cvt_pk_fp8_f32 v7, v28, v29 op_sel:[0,0,1]
	global_store_dwordx2 v[10:11], v[4:5], off
	global_store_dwordx2 v[10:11], v[6:7], off offset:128
	v_mov_b32_e32 v4, v165
	v_mov_b32_e32 v5, v165
	v_mov_b32_e32 v6, v165
	v_mov_b32_e32 v7, v165
	v_or_b32_e32 v10, 32, v2
	v_ashrrev_i32_e32 v11, 31, v10
	v_lshl_add_u64 v[12:13], v[10:11], 2, s[8:9]
	v_lshlrev_b64 v[10:11], 10, v[10:11]
	v_lshl_add_u64 v[10:11], s[88:89], 0, v[10:11]
	v_lshl_add_u64 v[10:11], v[10:11], 0, s[16:17]
	v_lshl_add_u64 v[10:11], v[10:11], 0, s[68:69]
	v_lshl_add_u64 v[10:11], v[10:11], 0, v[0:1]
	v_mul_f32_e32 v14, 0x3e800000, v231
	v_pk_mul_f32 v[18:19], v[140:141], v[14:15] op_sel_hi:[1,0]
	v_pk_mul_f32 v[22:23], v[136:137], v[14:15] op_sel_hi:[1,0]
	v_pk_mul_f32 v[16:17], v[142:143], v[14:15] op_sel_hi:[1,0]
	v_pk_mul_f32 v[20:21], v[138:139], v[14:15] op_sel_hi:[1,0]
	v_pk_mul_f32 v[24:25], v[134:135], v[14:15] op_sel_hi:[1,0]
	v_pk_mul_f32 v[26:27], v[132:133], v[14:15] op_sel_hi:[1,0]
	v_pk_mul_f32 v[28:29], v[130:131], v[14:15] op_sel_hi:[1,0]
	v_pk_mul_f32 v[14:15], v[128:129], v[14:15] op_sel_hi:[1,0]
	v_cvt_pk_fp8_f32 v4, v18, v19
	v_cvt_pk_fp8_f32 v5, v22, v23
	v_cvt_pk_fp8_f32 v6, v26, v27
	v_cvt_pk_fp8_f32 v7, v14, v15
	v_cvt_pk_fp8_f32 v4, v16, v17 op_sel:[0,0,1]
	v_cvt_pk_fp8_f32 v5, v20, v21 op_sel:[0,0,1]
	v_cvt_pk_fp8_f32 v6, v24, v25 op_sel:[0,0,1]
	v_cvt_pk_fp8_f32 v7, v28, v29 op_sel:[0,0,1]
	global_store_dwordx2 v[8:9], v[4:5], off
	global_store_dwordx2 v[8:9], v[6:7], off offset:128
	v_mov_b32_e32 v4, v165
	v_mov_b32_e32 v5, v165
	v_mov_b32_e32 v6, v165
	v_mov_b32_e32 v7, v165
	v_or_b32_e32 v8, 48, v2
	v_ashrrev_i32_e32 v9, 31, v8
	v_lshl_add_u64 v[12:13], v[8:9], 2, s[8:9]
	v_lshlrev_b64 v[8:9], 10, v[8:9]
	v_lshl_add_u64 v[8:9], s[88:89], 0, v[8:9]
	v_lshl_add_u64 v[8:9], v[8:9], 0, s[16:17]
	v_lshl_add_u64 v[8:9], v[8:9], 0, s[68:69]
	v_lshl_add_u64 v[8:9], v[8:9], 0, v[0:1]
	v_mul_f32_e32 v14, 0x3e800000, v232
	v_pk_mul_f32 v[18:19], v[124:125], v[14:15] op_sel_hi:[1,0]
	v_pk_mul_f32 v[22:23], v[120:121], v[14:15] op_sel_hi:[1,0]
	v_pk_mul_f32 v[16:17], v[126:127], v[14:15] op_sel_hi:[1,0]
	v_pk_mul_f32 v[20:21], v[122:123], v[14:15] op_sel_hi:[1,0]
	v_pk_mul_f32 v[24:25], v[118:119], v[14:15] op_sel_hi:[1,0]
	v_pk_mul_f32 v[26:27], v[116:117], v[14:15] op_sel_hi:[1,0]
	v_pk_mul_f32 v[28:29], v[114:115], v[14:15] op_sel_hi:[1,0]
	v_pk_mul_f32 v[14:15], v[112:113], v[14:15] op_sel_hi:[1,0]
	v_cvt_pk_fp8_f32 v4, v18, v19
	v_cvt_pk_fp8_f32 v5, v22, v23
	v_cvt_pk_fp8_f32 v6, v26, v27
	v_cvt_pk_fp8_f32 v7, v14, v15
	v_cvt_pk_fp8_f32 v4, v16, v17 op_sel:[0,0,1]
	v_cvt_pk_fp8_f32 v5, v20, v21 op_sel:[0,0,1]
	v_cvt_pk_fp8_f32 v6, v24, v25 op_sel:[0,0,1]
	v_cvt_pk_fp8_f32 v7, v28, v29 op_sel:[0,0,1]
	global_store_dwordx2 v[10:11], v[4:5], off
	global_store_dwordx2 v[10:11], v[6:7], off offset:128
	v_mov_b32_e32 v4, v165
	v_mov_b32_e32 v5, v165
	v_mov_b32_e32 v6, v165
	v_mov_b32_e32 v7, v165
	v_add_u32_e32 v10, 0x80, v2
	v_ashrrev_i32_e32 v11, 31, v10
	v_lshl_add_u64 v[12:13], v[10:11], 2, s[8:9]
	v_lshlrev_b64 v[10:11], 10, v[10:11]
	v_lshl_add_u64 v[10:11], s[88:89], 0, v[10:11]
	v_lshl_add_u64 v[10:11], v[10:11], 0, s[16:17]
	v_lshl_add_u64 v[10:11], v[10:11], 0, s[68:69]
	v_lshl_add_u64 v[10:11], v[10:11], 0, v[0:1]
	v_mul_f32_e32 v14, 0x3e800000, v233
	v_pk_mul_f32 v[18:19], v[108:109], v[14:15] op_sel_hi:[1,0]
	v_pk_mul_f32 v[22:23], v[104:105], v[14:15] op_sel_hi:[1,0]
	v_pk_mul_f32 v[16:17], v[110:111], v[14:15] op_sel_hi:[1,0]
	v_pk_mul_f32 v[20:21], v[106:107], v[14:15] op_sel_hi:[1,0]
	v_pk_mul_f32 v[24:25], v[102:103], v[14:15] op_sel_hi:[1,0]
	v_pk_mul_f32 v[26:27], v[100:101], v[14:15] op_sel_hi:[1,0]
	v_pk_mul_f32 v[28:29], v[98:99], v[14:15] op_sel_hi:[1,0]
	v_pk_mul_f32 v[14:15], v[96:97], v[14:15] op_sel_hi:[1,0]
	v_cvt_pk_fp8_f32 v4, v18, v19
	v_cvt_pk_fp8_f32 v5, v22, v23
	v_cvt_pk_fp8_f32 v6, v26, v27
	v_cvt_pk_fp8_f32 v7, v14, v15
	v_cvt_pk_fp8_f32 v4, v16, v17 op_sel:[0,0,1]
	v_cvt_pk_fp8_f32 v5, v20, v21 op_sel:[0,0,1]
	v_cvt_pk_fp8_f32 v6, v24, v25 op_sel:[0,0,1]
	v_cvt_pk_fp8_f32 v7, v28, v29 op_sel:[0,0,1]
	global_store_dwordx2 v[8:9], v[4:5], off
	global_store_dwordx2 v[8:9], v[6:7], off offset:128
	v_mov_b32_e32 v4, v165
	v_mov_b32_e32 v5, v165
	v_mov_b32_e32 v6, v165
	v_mov_b32_e32 v7, v165
	v_add_u32_e32 v8, 0x90, v2
	v_ashrrev_i32_e32 v9, 31, v8
	v_lshl_add_u64 v[12:13], v[8:9], 2, s[8:9]
	v_lshlrev_b64 v[8:9], 10, v[8:9]
	v_lshl_add_u64 v[8:9], s[88:89], 0, v[8:9]
	v_lshl_add_u64 v[8:9], v[8:9], 0, s[16:17]
	v_lshl_add_u64 v[8:9], v[8:9], 0, s[68:69]
	v_lshl_add_u64 v[8:9], v[8:9], 0, v[0:1]
	v_mul_f32_e32 v14, 0x3e800000, v234
	v_pk_mul_f32 v[18:19], v[92:93], v[14:15] op_sel_hi:[1,0]
	v_pk_mul_f32 v[22:23], v[88:89], v[14:15] op_sel_hi:[1,0]
	v_pk_mul_f32 v[16:17], v[94:95], v[14:15] op_sel_hi:[1,0]
	v_pk_mul_f32 v[20:21], v[90:91], v[14:15] op_sel_hi:[1,0]
	v_pk_mul_f32 v[24:25], v[86:87], v[14:15] op_sel_hi:[1,0]
	v_pk_mul_f32 v[26:27], v[84:85], v[14:15] op_sel_hi:[1,0]
	v_pk_mul_f32 v[28:29], v[82:83], v[14:15] op_sel_hi:[1,0]
	v_pk_mul_f32 v[14:15], v[80:81], v[14:15] op_sel_hi:[1,0]
	v_cvt_pk_fp8_f32 v4, v18, v19
	v_cvt_pk_fp8_f32 v5, v22, v23
	v_cvt_pk_fp8_f32 v6, v26, v27
	v_cvt_pk_fp8_f32 v7, v14, v15
	v_cvt_pk_fp8_f32 v4, v16, v17 op_sel:[0,0,1]
	v_cvt_pk_fp8_f32 v5, v20, v21 op_sel:[0,0,1]
	v_cvt_pk_fp8_f32 v6, v24, v25 op_sel:[0,0,1]
	v_cvt_pk_fp8_f32 v7, v28, v29 op_sel:[0,0,1]
	global_store_dwordx2 v[10:11], v[4:5], off
	global_store_dwordx2 v[10:11], v[6:7], off offset:128
	v_mov_b32_e32 v4, v165
	v_mov_b32_e32 v5, v165
	v_mov_b32_e32 v6, v165
	v_mov_b32_e32 v7, v165
	v_add_u32_e32 v10, 0xa0, v2
	v_ashrrev_i32_e32 v11, 31, v10
	v_lshl_add_u64 v[12:13], v[10:11], 2, s[8:9]
	v_add_u32_e32 v2, 0xb0, v2
	v_mul_f32_e32 v14, 0x3e800000, v235
	v_pk_mul_f32 v[18:19], v[76:77], v[14:15] op_sel_hi:[1,0]
	v_pk_mul_f32 v[22:23], v[72:73], v[14:15] op_sel_hi:[1,0]
	v_pk_mul_f32 v[16:17], v[78:79], v[14:15] op_sel_hi:[1,0]
	v_pk_mul_f32 v[20:21], v[74:75], v[14:15] op_sel_hi:[1,0]
	v_pk_mul_f32 v[24:25], v[70:71], v[14:15] op_sel_hi:[1,0]
	v_pk_mul_f32 v[26:27], v[68:69], v[14:15] op_sel_hi:[1,0]
	v_pk_mul_f32 v[28:29], v[66:67], v[14:15] op_sel_hi:[1,0]
	v_pk_mul_f32 v[14:15], v[64:65], v[14:15] op_sel_hi:[1,0]
	v_cvt_pk_fp8_f32 v4, v18, v19
	v_cvt_pk_fp8_f32 v5, v22, v23
	v_cvt_pk_fp8_f32 v6, v26, v27
	v_cvt_pk_fp8_f32 v7, v14, v15
	v_cvt_pk_fp8_f32 v4, v16, v17 op_sel:[0,0,1]
	v_cvt_pk_fp8_f32 v5, v20, v21 op_sel:[0,0,1]
	v_cvt_pk_fp8_f32 v6, v24, v25 op_sel:[0,0,1]
	v_cvt_pk_fp8_f32 v7, v28, v29 op_sel:[0,0,1]
	global_store_dwordx2 v[8:9], v[4:5], off
	global_store_dwordx2 v[8:9], v[6:7], off offset:128
	v_mov_b32_e32 v4, v165
	v_mov_b32_e32 v5, v165
	v_mov_b32_e32 v6, v165
	v_mov_b32_e32 v7, v165
	v_lshlrev_b64 v[8:9], 10, v[10:11]
	v_lshl_add_u64 v[8:9], s[88:89], 0, v[8:9]
	v_lshl_add_u64 v[8:9], v[8:9], 0, s[16:17]
	v_lshl_add_u64 v[8:9], v[8:9], 0, s[68:69]
	v_ashrrev_i32_e32 v3, 31, v2
	v_lshl_add_u64 v[8:9], v[8:9], 0, v[0:1]
	v_lshl_add_u64 v[10:11], v[2:3], 2, s[8:9]
	v_lshlrev_b64 v[2:3], 10, v[2:3]
	v_lshl_add_u64 v[2:3], s[88:89], 0, v[2:3]
	v_lshl_add_u64 v[2:3], v[2:3], 0, s[16:17]
	v_lshl_add_u64 v[2:3], v[2:3], 0, s[68:69]
	v_lshl_add_u64 v[0:1], v[2:3], 0, v[0:1]
	v_mul_f32_e32 v12, 0x3e800000, v236
	v_pk_mul_f32 v[16:17], v[60:61], v[12:13] op_sel_hi:[1,0]
	v_pk_mul_f32 v[20:21], v[56:57], v[12:13] op_sel_hi:[1,0]
	v_pk_mul_f32 v[14:15], v[62:63], v[12:13] op_sel_hi:[1,0]
	v_pk_mul_f32 v[18:19], v[58:59], v[12:13] op_sel_hi:[1,0]
	v_pk_mul_f32 v[22:23], v[54:55], v[12:13] op_sel_hi:[1,0]
	v_pk_mul_f32 v[24:25], v[52:53], v[12:13] op_sel_hi:[1,0]
	v_pk_mul_f32 v[26:27], v[50:51], v[12:13] op_sel_hi:[1,0]
	v_pk_mul_f32 v[12:13], v[48:49], v[12:13] op_sel_hi:[1,0]
	v_cvt_pk_fp8_f32 v4, v16, v17
	v_cvt_pk_fp8_f32 v5, v20, v21
	v_cvt_pk_fp8_f32 v6, v24, v25
	v_cvt_pk_fp8_f32 v7, v12, v13
	v_cvt_pk_fp8_f32 v4, v14, v15 op_sel:[0,0,1]
	v_cvt_pk_fp8_f32 v5, v18, v19 op_sel:[0,0,1]
	v_cvt_pk_fp8_f32 v6, v22, v23 op_sel:[0,0,1]
	v_cvt_pk_fp8_f32 v7, v26, v27 op_sel:[0,0,1]
	global_store_dwordx2 v[8:9], v[4:5], off
	global_store_dwordx2 v[8:9], v[6:7], off offset:128
	v_mov_b32_e32 v4, v165
	v_mov_b32_e32 v5, v165
	v_mov_b32_e32 v6, v165
	v_mov_b32_e32 v7, v165
	v_mul_f32_e32 v8, 0x3e800000, v237
	v_pk_mul_f32 v[12:13], v[44:45], v[8:9] op_sel_hi:[1,0]
	v_pk_mul_f32 v[16:17], v[40:41], v[8:9] op_sel_hi:[1,0]
	v_pk_mul_f32 v[10:11], v[46:47], v[8:9] op_sel_hi:[1,0]
	v_pk_mul_f32 v[14:15], v[42:43], v[8:9] op_sel_hi:[1,0]
	v_pk_mul_f32 v[18:19], v[38:39], v[8:9] op_sel_hi:[1,0]
	v_pk_mul_f32 v[20:21], v[36:37], v[8:9] op_sel_hi:[1,0]
	v_pk_mul_f32 v[22:23], v[34:35], v[8:9] op_sel_hi:[1,0]
	v_pk_mul_f32 v[8:9], v[32:33], v[8:9] op_sel_hi:[1,0]
	v_cvt_pk_fp8_f32 v4, v12, v13
	v_cvt_pk_fp8_f32 v5, v16, v17
	v_cvt_pk_fp8_f32 v6, v20, v21
	v_cvt_pk_fp8_f32 v7, v8, v9
	v_cvt_pk_fp8_f32 v4, v10, v11 op_sel:[0,0,1]
	v_cvt_pk_fp8_f32 v5, v14, v15 op_sel:[0,0,1]
	v_cvt_pk_fp8_f32 v6, v18, v19 op_sel:[0,0,1]
	v_cvt_pk_fp8_f32 v7, v22, v23 op_sel:[0,0,1]
	global_store_dwordx2 v[0:1], v[4:5], off
	global_store_dwordx2 v[0:1], v[6:7], off offset:128
	s_cbranch_vccnz .LBB0_1318
	s_andn2_b64 vcc, exec, s[6:7]
	s_cbranch_vccnz .LBB0_1317
	s_barrier
	s_branch .LBB0_1317
